# sliding-window branch loop hand-scheduled like the selected branch; both with 2-deep register prefetch of K/V blocks
# speedup vs baseline: 1.0109x; 1.0088x over previous
; #define LAS __attribute__((address_space(3)))
; template <int MODE  > ...
;     int lane = lane_in, tid = tid_in;
;     asm volatile("" : "+v"(lane), "+v"(tid));
;     constexpr bool NEEDV = (MODE != 3);
;     constexpr bool CMPM = (MODE == 0 || MODE == 3);
;     const int col = lane & 31, h = lane >> 5;
;     const int skey = tid >> 3, schunk = tid & 7;
;     unsigned long long rem = blockmask;
;     if (!rem) return;
;     int j = 63 - __builtin_clzll(rem); rem &= ~(1ull << j);
;     u32x4 kreg, vreg;
;     kreg = *(const u32x4*)(Kg + (size_t)(64 * j + skey) * 128 + schunk * 8);
;     if (NEEDV) vreg = *(const u32x4*)(Vg + (size_t)(64 * j + skey) * 128 + schunk * 8);
;     int cur = 0;
;     {
;         LAS bf16_t* kb = (LAS bf16_t*)(lds + A_KBUF) + cur * 64 * KPITCH;
;         *(LAS u32x4*)(kb + skey * KPITCH + schunk * 8) = kreg;
;         if (NEEDV) { LAS bf16_t* vb = (LAS bf16_t*)(lds + A_VBUF) + cur * 64 * VPITCH;
;             *(LAS u32x4*)(vb + skey * VPITCH + schunk * 8) = vreg; }
;     }
;     __syncthreads();
;     for (;;) {
;         const bool has_next = rem != 0ull; int jn = 0;
;         if (has_next) { jn = 63 - __builtin_clzll(rem); rem &= ~(1ull << jn);
;             kreg = *(const u32x4*)(Kg + (size_t)(64 * jn + skey) * 128 + schunk * 8);
;             if (NEEDV) vreg = *(const u32x4*)(Vg + (size_t)(64 * jn + skey) * 128 + schunk * 8); }
.LBB0_246:
	s_lshl_b32 s4, s68, 19
	s_or_b32 s22, s62, s4
	v_mov_b32_e32 v1, v179
	v_mov_b32_e32 v2, v178
	s_cmp_eq_u64 s[14:15], 0
	v_add_f32_e32 v187, v186, v186
	s_waitcnt vmcnt(0)
	v_fma_f32 v163, 2.0, v186, v186
	s_cbranch_scc1 .LBB0_263
	s_lshl_b32 s16, s22, 1
	s_add_u32 s4, s43, s16
	s_addc_u32 s5, s44, 0
	s_add_u32 s16, s45, s16
	s_flbit_i32_b64 s18, s[14:15]
	v_ashrrev_i32_e32 v164, 3, v2
	s_addc_u32 s17, s46, 0
	s_xor_b32 s68, s18, 63
	v_lshl_add_u32 v4, s68, 6, v164
	v_ashrrev_i32_e32 v5, 31, v4
	v_lshlrev_b64 v[4:5], 8, v[4:5]
	v_lshlrev_b32_e32 v2, 4, v2
	v_lshl_add_u64 v[6:7], s[16:17], 0, v[4:5]
	v_and_b32_e32 v16, 0x70, v2
	v_mov_b32_e32 v17, v0
	v_lshl_add_u64 v[2:3], v[6:7], 0, v[16:17]
	v_lshl_add_u64 v[4:5], s[4:5], 0, v[4:5]
	v_lshl_add_u64 v[4:5], v[4:5], 0, v[16:17]
	global_load_dwordx4 v[130:133], v[2:3], off
	global_load_dwordx4 v[134:137], v[4:5], off
	v_ashrrev_i32_e32 v18, 5, v1
	v_lshrrev_b32_e32 v34, 2, v1
	v_lshlrev_b32_e32 v37, 2, v18
	v_and_or_b32 v34, v34, 3, v37
	v_and_b32_e32 v19, 31, v1
	v_and_b32_e32 v21, 16, v1
	v_lshlrev_b32_e32 v22, 3, v1
	s_movk_i32 s18, 0x90
	v_mul_lo_u32 v34, v34, s70
	v_lshlrev_b32_e32 v20, 2, v1
	v_mov_b32_e32 v14, v0
	v_mov_b32_e32 v15, v0
	v_mul_lo_u32 v35, v164, s18
	v_mul_lo_u32 v36, v164, s70
	v_mul_u32_u24_e32 v38, 0x90, v19
	v_lshlrev_b32_e32 v39, 1, v21
	v_and_b32_e32 v40, 24, v22
	v_lshlrev_b32_e32 v41, 4, v18
	v_add_u32_e32 v34, 0, v34
	v_mov_b32_e32 v1, v0
	v_mov_b32_e32 v2, v0
	v_mov_b32_e32 v3, v0
	v_mov_b32_e32 v4, v0
	v_mov_b32_e32 v5, v0
	v_mov_b32_e32 v6, v0
	v_mov_b32_e32 v7, v0
	v_mov_b32_e32 v8, v0
	v_mov_b32_e32 v9, v0
	v_mov_b32_e32 v10, v0
	v_mov_b32_e32 v11, v0
	v_mov_b32_e32 v12, v0
	v_mov_b32_e32 v13, v0
	v_bitop3_b32 v165, v20, s66, v240 bitop3:0x6c
	v_mov_b64_e32 v[32:33], v[14:15]
	v_add3_u32 v166, 0, v35, v16
	v_add3_u32 v167, 0, v36, v16
	v_sub_u32_e32 v190, v37, v188
	v_add3_u32 v191, 0, v38, v41
	v_lshl_add_u64 v[142:143], s[4:5], 0, v[16:17]
	s_lshl_b64 s[4:5], 1, s68
	v_add3_u32 v192, v34, v39, v40
	v_mov_b64_e32 v[48:49], v[14:15]
	s_mov_b32 s23, 0
	v_mov_b32_e32 v194, 0xefa18f08
	v_mov_b32_e32 v193, 0
	v_mov_b64_e32 v[30:31], v[12:13]
	v_mov_b64_e32 v[28:29], v[10:11]
	v_mov_b64_e32 v[26:27], v[8:9]
	v_mov_b64_e32 v[24:25], v[6:7]
	v_mov_b64_e32 v[22:23], v[4:5]
	v_mov_b64_e32 v[20:21], v[2:3]
	v_mov_b64_e32 v[18:19], v[0:1]
	v_lshl_add_u64 v[160:161], s[16:17], 0, v[16:17]
	s_andn2_b64 s[14:15], s[14:15], s[4:5]
	v_mov_b64_e32 v[46:47], v[12:13]
	v_mov_b64_e32 v[44:45], v[10:11]
	v_mov_b64_e32 v[42:43], v[8:9]
	v_mov_b64_e32 v[40:41], v[6:7]
	v_mov_b64_e32 v[38:39], v[4:5]
	v_mov_b64_e32 v[36:37], v[2:3]
	v_mov_b64_e32 v[34:35], v[0:1]
	s_mov_b64 s[18:19], s[14:15]
	s_mov_b32 s20, 0
	s_cmp_eq_u64 s[18:19], 0
	s_cbranch_scc1 .Lm1_pre_nob1
	s_flbit_i32_b64 s62, s[18:19]
	s_xor_b32 s62, s62, 63
	s_lshl_b64 s[4:5], 1, s62
	s_andn2_b64 s[18:19], s[18:19], s[4:5]
	v_lshl_add_u32 v2, s62, 6, v164
	v_ashrrev_i32_e32 v3, 31, v2
	v_lshlrev_b64 v[2:3], 8, v[2:3]
	v_lshl_add_u64 v[4:5], v[160:161], 0, v[2:3]
	v_lshl_add_u64 v[2:3], v[142:143], 0, v[2:3]
	global_load_dwordx4 v[226:229], v[4:5], off
	global_load_dwordx4 v[230:233], v[2:3], off
	s_mov_b32 s20, 1
	s_waitcnt vmcnt(2)
	s_branch .Lm1_pre_w

; #define LAS __attribute__((address_space(3)))
; template <int MODE  > ...
;     ...
;         const bool has_next = rem != 0ull; int jn = 0;
;         if (has_next) { jn = 63 - __builtin_clzll(rem); rem &= ~(1ull << jn);
;             kreg = *(const u32x4*)(Kg + (size_t)(64 * jn + skey) * 128 + schunk * 8);
;             if (NEEDV) vreg = *(const u32x4*)(Vg + (size_t)(64 * jn + skey) * 128 + schunk * 8); }
;         const bool selbit = (MODE == 1) ? (((selmask >> j) & 1ull) != 0ull) : true;
;         bool active = true;
;         if (MODE == 1) active = __builtin_amdgcn_ballot_w64(selbit) != 0ull;
;         if (active) {
;             const LAS bf16_t* kb = (const LAS bf16_t*)(lds + A_KBUF) + cur * 64 * KPITCH;
;             constexpr int STEP = CMPM ? 16 : 1;
;             const int Bint = CMPM ? (1024 * j + 31 - t + 64 * h) : (64 * j - t + 4 * h);
;             const float sl = slope2 * (float)STEP;
;             const float mref = st.m; const bool fresh = !(mref > -1e28f);
;             const float mest = fresh ? 0.f : mref;
;             const float basef = selbit ? (slope2 * (float)Bint - mest) : -1e30f;
;             int ptype;
;             if (MODE == 1) ptype = (j == cblk) ? 1 : 0;
;             else if (MODE == 2) ptype = (j == cblk) ? 1 : ((j == cblk - 8) ? 2 : 0);
;             else ptype = (64 * j + 63 <= 4 * cblk - 2) ? 0 : 1;
;             f32x16 s0, s1;
;             { const float sl2 = sl + sl, sl3 = sl2 + sl;
; #pragma unroll
;               for (int g8 = 0; g8 < 4; ++g8) {
;                   const float b0 = __builtin_fmaf(sl, (float)(8 * g8), basef), b1 = __builtin_fmaf(sl, (float)(8 * g8 + 32), basef);
;                   s0[4 * g8] = b0; s0[4 * g8 + 1] = b0 + sl; s0[4 * g8 + 2] = b0 + sl2; s0[4 * g8 + 3] = b0 + sl3;
;                   s1[4 * g8] = b1; s1[4 * g8 + 1] = b1 + sl; s1[4 * g8 + 2] = b1 + sl2; s1[4 * g8 + 3] = b1 + sl3;
;               } }
;             if (ptype == 1) {
;                 const float thr = 0.5f * slope2 - mest;
; #pragma unroll
;                 for (int i = 0; i < 16; ++i) { s0[i] = (s0[i] < thr) ? s0[i] : -1e30f; s1[i] = (s1[i] < thr) ? s1[i] : -1e30f; }
.Lm1_pre_w:
	s_waitcnt lgkmcnt(0)
	ds_write_b128 v166, v[130:133]
	ds_write_b128 v167, v[134:137] offset:18432
	s_waitcnt lgkmcnt(0)
	s_barrier
.LBB0_248:
	s_mov_b32 s21, 0
	s_cmp_eq_u64 s[18:19], 0
	s_cbranch_scc1 .Lm1_noload
	s_flbit_i32_b64 s4, s[18:19]
	s_xor_b32 s4, s4, 63
	s_lshl_b64 s[16:17], 1, s4
	s_andn2_b64 s[18:19], s[18:19], s[16:17]
	s_mov_b32 s21, 1
	v_lshl_add_u32 v2, s4, 6, v164
	v_ashrrev_i32_e32 v3, 31, v2
	v_lshlrev_b64 v[2:3], 8, v[2:3]
	v_lshl_add_u64 v[4:5], v[160:161], 0, v[2:3]
	v_lshl_add_u64 v[2:3], v[142:143], 0, v[2:3]
	s_cmp_eq_u32 s23, 0
	s_cbranch_scc0 .Lm1_loadB
	global_load_dwordx4 v[130:133], v[4:5], off
	global_load_dwordx4 v[134:137], v[2:3], off
	s_branch .Lm1_noload
.Lm1_loadB:
	global_load_dwordx4 v[226:229], v[4:5], off
	global_load_dwordx4 v[230:233], v[2:3], off
.Lm1_noload:
.LBB0_250:
	v_lshrrev_b64 v[2:3], s68, v[140:141]
	v_and_b32_e32 v1, 1, v2
	v_cmp_eq_u32_e64 s[16:17], 1, v1
	v_cmp_ne_u32_e32 vcc, 0, v1
	s_cbranch_vccz .LBB0_258
	s_mul_i32 vcc_lo, s23, 0x2400
	s_mul_i32 vcc_hi, s23, 0x3000
	v_add_u32_e32 v223, vcc_lo, v191
	v_add_u32_e32 v222, vcc_hi, v192
	ds_read_b128 v[66:69], v223
	ds_read_b128 v[70:73], v223 offset:4608
	ds_read_b128 v[74:77], v223 offset:32
	ds_read_b128 v[78:81], v223 offset:4640
	ds_read_b128 v[82:85], v223 offset:64
	ds_read_b128 v[86:89], v223 offset:4672
	ds_read_b128 v[90:93], v223 offset:96
	ds_read_b128 v[94:97], v223 offset:4704
	v_lshl_add_u32 v1, s68, 6, v190
	v_cvt_f32_i32_e32 v2, v1
	v_cmp_nlt_f32_e64 s[14:15], s71, v194
	s_cmp_lg_u32 s68, s83
	s_nop 0
	v_cndmask_b32_e64 v1, v194, 0, s[14:15]
	v_fma_f32 v2, v186, v2, -v1
	v_cndmask_b32_e64 v14, v241, v2, s[16:17]
	v_fma_f32 v50, 0, v186, v14
	v_fmamk_f32 v54, v186, 0x41000000, v14
	v_fmamk_f32 v58, v186, 0x41800000, v14
	v_fmamk_f32 v62, v186, 0x41c00000, v14
	v_fmamk_f32 v2, v186, 0x42000000, v14
	v_fmamk_f32 v6, v186, 0x42200000, v14
	v_fmamk_f32 v10, v186, 0x42400000, v14
	v_fmac_f32_e32 v14, 0x42600000, v186
	v_add_f32_e32 v51, v186, v50
	v_add_f32_e32 v52, v187, v50
	v_add_f32_e32 v53, v163, v50
	v_add_f32_e32 v55, v186, v54
	v_add_f32_e32 v56, v187, v54
	v_add_f32_e32 v57, v163, v54
	v_add_f32_e32 v59, v186, v58
	v_add_f32_e32 v60, v187, v58
	v_add_f32_e32 v61, v163, v58
	v_add_f32_e32 v63, v186, v62
	v_add_f32_e32 v64, v187, v62
	v_add_f32_e32 v65, v163, v62
	v_add_f32_e32 v3, v186, v2
	v_add_f32_e32 v4, v187, v2
	v_add_f32_e32 v5, v163, v2
	v_add_f32_e32 v7, v186, v6
	v_add_f32_e32 v8, v187, v6
	v_add_f32_e32 v9, v163, v6
	v_add_f32_e32 v11, v186, v10
	v_add_f32_e32 v12, v187, v10
	v_add_f32_e32 v13, v163, v10
	v_add_f32_e32 v15, v186, v14
	v_add_f32_e32 v16, v187, v14
	v_add_f32_e32 v17, v163, v14
	s_cbranch_scc1 .Lm1_qk
	v_sub_f32_e32 v224, v189, v1
	v_cmp_lt_f32_e32 vcc, v50, v224
	s_nop 1
	v_cndmask_b32_e32 v50, v241, v50, vcc
	v_cmp_lt_f32_e32 vcc, v51, v224
	s_nop 1
	v_cndmask_b32_e32 v51, v241, v51, vcc
	v_cmp_lt_f32_e32 vcc, v52, v224
	s_nop 1
	v_cndmask_b32_e32 v52, v241, v52, vcc
	v_cmp_lt_f32_e32 vcc, v53, v224
	s_nop 1
	v_cndmask_b32_e32 v53, v241, v53, vcc
	v_cmp_lt_f32_e32 vcc, v54, v224
	s_nop 1
	v_cndmask_b32_e32 v54, v241, v54, vcc
	v_cmp_lt_f32_e32 vcc, v55, v224
	s_nop 1
	v_cndmask_b32_e32 v55, v241, v55, vcc
	v_cmp_lt_f32_e32 vcc, v56, v224
	s_nop 1
	v_cndmask_b32_e32 v56, v241, v56, vcc
	v_cmp_lt_f32_e32 vcc, v57, v224
	s_nop 1
	v_cndmask_b32_e32 v57, v241, v57, vcc
	v_cmp_lt_f32_e32 vcc, v58, v224
	s_nop 1
	v_cndmask_b32_e32 v58, v241, v58, vcc
	v_cmp_lt_f32_e32 vcc, v59, v224
	s_nop 1
	v_cndmask_b32_e32 v59, v241, v59, vcc
	v_cmp_lt_f32_e32 vcc, v60, v224
	s_nop 1
	v_cndmask_b32_e32 v60, v241, v60, vcc
	v_cmp_lt_f32_e32 vcc, v61, v224
	s_nop 1
	v_cndmask_b32_e32 v61, v241, v61, vcc
	v_cmp_lt_f32_e32 vcc, v62, v224
	s_nop 1
	v_cndmask_b32_e32 v62, v241, v62, vcc
	v_cmp_lt_f32_e32 vcc, v63, v224
	s_nop 1
	v_cndmask_b32_e32 v63, v241, v63, vcc
	v_cmp_lt_f32_e32 vcc, v64, v224
	s_nop 1
	v_cndmask_b32_e32 v64, v241, v64, vcc
	v_cmp_lt_f32_e32 vcc, v65, v224
	s_nop 1
	v_cndmask_b32_e32 v65, v241, v65, vcc
	v_cmp_lt_f32_e32 vcc, v2, v224
	s_nop 1
	v_cndmask_b32_e32 v2, v241, v2, vcc
	v_cmp_lt_f32_e32 vcc, v3, v224
	s_nop 1
	v_cndmask_b32_e32 v3, v241, v3, vcc
	v_cmp_lt_f32_e32 vcc, v4, v224
	s_nop 1
	v_cndmask_b32_e32 v4, v241, v4, vcc
	v_cmp_lt_f32_e32 vcc, v5, v224
	s_nop 1
	v_cndmask_b32_e32 v5, v241, v5, vcc
	v_cmp_lt_f32_e32 vcc, v6, v224
	s_nop 1
	v_cndmask_b32_e32 v6, v241, v6, vcc
	v_cmp_lt_f32_e32 vcc, v7, v224
	s_nop 1
	v_cndmask_b32_e32 v7, v241, v7, vcc
	v_cmp_lt_f32_e32 vcc, v8, v224
	s_nop 1
	v_cndmask_b32_e32 v8, v241, v8, vcc
	v_cmp_lt_f32_e32 vcc, v9, v224
	s_nop 1
	v_cndmask_b32_e32 v9, v241, v9, vcc
	v_cmp_lt_f32_e32 vcc, v10, v224
	s_nop 1
	v_cndmask_b32_e32 v10, v241, v10, vcc
	v_cmp_lt_f32_e32 vcc, v11, v224
	s_nop 1
	v_cndmask_b32_e32 v11, v241, v11, vcc
	v_cmp_lt_f32_e32 vcc, v12, v224
	s_nop 1
	v_cndmask_b32_e32 v12, v241, v12, vcc
	v_cmp_lt_f32_e32 vcc, v13, v224
	s_nop 1
	v_cndmask_b32_e32 v13, v241, v13, vcc
	v_cmp_lt_f32_e32 vcc, v14, v224
	s_nop 1
	v_cndmask_b32_e32 v14, v241, v14, vcc
	v_cmp_lt_f32_e32 vcc, v15, v224
	s_nop 1
	v_cndmask_b32_e32 v15, v241, v15, vcc
	v_cmp_lt_f32_e32 vcc, v16, v224
	s_nop 1
	v_cndmask_b32_e32 v16, v241, v16, vcc
	v_cmp_lt_f32_e32 vcc, v17, v224
	s_nop 1
	v_cndmask_b32_e32 v17, v241, v17, vcc

; #define LAS __attribute__((address_space(3)))
; template <int MODE  > ...
;     ...
;         if (has_next) {
;             LAS bf16_t* kb = (LAS bf16_t*)(lds + A_KBUF) + (cur ^ 1) * 64 * KPITCH;
;             *(LAS u32x4*)(kb + skey * KPITCH + schunk * 8) = kreg;
;             if (NEEDV) { LAS bf16_t* vb = (LAS bf16_t*)(lds + A_VBUF) + (cur ^ 1) * 64 * VPITCH;
;                 *(LAS u32x4*)(vb + skey * VPITCH + schunk * 8) = vreg; }
;         }
.LBB0_258:
	s_cmp_eq_u32 s20, 0
	s_cbranch_scc1 .LBB0_260
	s_lshl_b32 s14, s23, 6
	s_xor_b32 s14, s14, 64
	s_mul_i32 s15, s14, 0x90
	v_add_u32_e32 v1, s15, v166
	s_mulk_i32 s14, 0xc0
	v_add_u32_e32 v2, s14, v167
	s_cmp_eq_u32 s21, 0
	s_cbranch_scc1 .Lm1_w0
	s_waitcnt vmcnt(2)
	s_branch .Lm1_w1

; #define LAS __attribute__((address_space(3)))
; template <int MODE  > ...
;     ...
;         if (has_next) {
;             LAS bf16_t* kb = (LAS bf16_t*)(lds + A_KBUF) + (cur ^ 1) * 64 * KPITCH;
;             *(LAS u32x4*)(kb + skey * KPITCH + schunk * 8) = kreg;
;             if (NEEDV) { LAS bf16_t* vb = (LAS bf16_t*)(lds + A_VBUF) + (cur ^ 1) * 64 * VPITCH;
;                 *(LAS u32x4*)(vb + skey * VPITCH + schunk * 8) = vreg; }
;         }
;         __syncthreads();
;         if (!has_next) break;
;         j = jn; cur ^= 1;
;     }
.Lm1_w1:
	s_cmp_eq_u32 s23, 0
	s_cbranch_scc0 .Lm1_stA
	ds_write_b128 v1, v[226:229]
	ds_write_b128 v2, v[230:233] offset:18432
	s_branch .LBB0_260
.Lm1_stA:
	ds_write_b128 v1, v[130:133]
	ds_write_b128 v2, v[134:137] offset:18432
.LBB0_260:
	s_xor_b32 s23, s23, 1
	s_waitcnt lgkmcnt(0)
	s_barrier
	s_cmp_eq_u32 s20, 0
	s_cbranch_scc1 .Lm1_exit
	s_mov_b32 s68, s62
	s_mov_b32 s62, s4
	s_mov_b32 s20, s21
	s_branch .LBB0_248

; #define LAS __attribute__((address_space(3)))
; template <int MODE  > ...
;     ...
;     unsigned long long rem = blockmask;
;     if (!rem) return;
;     int j = 63 - __builtin_clzll(rem); rem &= ~(1ull << j);
;     u32x4 kreg, vreg;
;     kreg = *(const u32x4*)(Kg + (size_t)(64 * j + skey) * 128 + schunk * 8);
;     if (NEEDV) vreg = *(const u32x4*)(Vg + (size_t)(64 * j + skey) * 128 + schunk * 8);
;     int cur = 0;
;     {
;         LAS bf16_t* kb = (LAS bf16_t*)(lds + A_KBUF) + cur * 64 * KPITCH;
;         *(LAS u32x4*)(kb + skey * KPITCH + schunk * 8) = kreg;
;         if (NEEDV) { LAS bf16_t* vb = (LAS bf16_t*)(lds + A_VBUF) + cur * 64 * VPITCH;
;             *(LAS u32x4*)(vb + skey * VPITCH + schunk * 8) = vreg; }
;     }
;     __syncthreads();
;     for (;;) {
;         const bool has_next = rem != 0ull; int jn = 0;
;         if (has_next) { jn = 63 - __builtin_clzll(rem); rem &= ~(1ull << jn);
;             kreg = *(const u32x4*)(Kg + (size_t)(64 * jn + skey) * 128 + schunk * 8);
;             if (NEEDV) vreg = *(const u32x4*)(Vg + (size_t)(64 * jn + skey) * 128 + schunk * 8); }
; __device__ __forceinline__ void attn_unit(unsigned char* ws, LAS unsigned char* lds, int b, int g, int c, const int tid) {
;     ...
;     { const float gate1 = ((const float*)(ws + WS_G))[row * 32 + head * 3 + 1]; const float sc = st.l > 0.f ? gate1 / st.l : 0.f;
; #pragma unroll
;       for (int i = 0; i < 16; ++i) { outl[i * 512] += st.o0[i] * sc; outl[(16 + i) * 512] += st.o1[i] * sc; } }
;     st.m = -1e29f; st.l = 0.f; st.o0 = (f32x16){}; st.o1 = (f32x16){};
;     { const int jlo = c >= 8 ? c - 8 : 0; const unsigned long long upto = (c >= 63) ? ~0ull : ((1ull << (c + 1)) - 1ull);
;       const unsigned long long winmask = upto & ~((1ull << jlo) - 1ull);
;       attn_pass<2>(lds, (const bf16_t*)(ws + WS_KW) + boff, (const bf16_t*)(ws + WS_VW) + boff, winmask, qf, st, t, slope2, 0ull, w, lane, tid, c); }
.LBB0_266:
	s_or_b64 exec, exec, s[4:5]
	ds_read2st64_b32 v[2:3], v199 offset1:8
	ds_read2st64_b32 v[4:5], v199 offset0:128 offset1:136
	s_add_i32 s4, s83, 1
	s_lshl_b64 s[4:5], -1, s4
	s_not_b64 s[4:5], s[4:5]
	s_waitcnt lgkmcnt(0)
	v_fma_f32 v2, v18, v1, v2
	v_fma_f32 v4, v34, v1, v4
	v_fmac_f32_e32 v3, v19, v1
	v_fmac_f32_e32 v5, v35, v1
	ds_write2st64_b32 v199, v2, v3 offset1:8
	ds_write2st64_b32 v199, v4, v5 offset0:128 offset1:136
	ds_read2st64_b32 v[2:3], v199 offset0:16 offset1:24
	ds_read2st64_b32 v[4:5], v199 offset0:144 offset1:152
	s_cmp_lt_u32 s83, 63
	s_cselect_b32 s5, s5, -1
	s_cselect_b32 s4, s4, -1
	s_waitcnt lgkmcnt(0)
	v_fma_f32 v2, v20, v1, v2
	v_fma_f32 v4, v36, v1, v4
	v_fmac_f32_e32 v3, v21, v1
	v_fmac_f32_e32 v5, v37, v1
	ds_write2st64_b32 v199, v2, v3 offset0:16 offset1:24
	ds_write2st64_b32 v199, v4, v5 offset0:144 offset1:152
	ds_read2st64_b32 v[2:3], v199 offset0:32 offset1:40
	ds_read2st64_b32 v[4:5], v199 offset0:160 offset1:168
	v_mov_b32_e32 v34, v178
	v_mov_b32_e32 v16, 0
	v_mov_b32_e32 v15, 0
	s_waitcnt lgkmcnt(0)
	v_fma_f32 v2, v22, v1, v2
	v_fma_f32 v4, v38, v1, v4
	v_fmac_f32_e32 v3, v23, v1
	v_fmac_f32_e32 v5, v39, v1
	ds_write2st64_b32 v199, v2, v3 offset0:32 offset1:40
	ds_write2st64_b32 v199, v4, v5 offset0:160 offset1:168
	ds_read2st64_b32 v[2:3], v199 offset0:48 offset1:56
	ds_read2st64_b32 v[4:5], v199 offset0:176 offset1:184
	v_mov_b32_e32 v14, 0
	v_mov_b32_e32 v13, 0
	v_mov_b32_e32 v12, 0
	s_waitcnt lgkmcnt(0)
	v_fma_f32 v2, v24, v1, v2
	v_fma_f32 v4, v40, v1, v4
	v_fmac_f32_e32 v3, v25, v1
	v_fmac_f32_e32 v5, v41, v1
	ds_write2st64_b32 v199, v2, v3 offset0:48 offset1:56
	ds_write2st64_b32 v199, v4, v5 offset0:176 offset1:184
	ds_read2st64_b32 v[2:3], v199 offset0:64 offset1:72
	ds_read2st64_b32 v[4:5], v199 offset0:192 offset1:200
	v_mov_b32_e32 v11, 0
	v_mov_b32_e32 v10, 0
	v_mov_b32_e32 v9, 0
	s_waitcnt lgkmcnt(0)
	v_fma_f32 v2, v26, v1, v2
	v_fma_f32 v4, v42, v1, v4
	v_fmac_f32_e32 v3, v27, v1
	v_fmac_f32_e32 v5, v43, v1
	ds_write2st64_b32 v199, v2, v3 offset0:64 offset1:72
	ds_write2st64_b32 v199, v4, v5 offset0:192 offset1:200
	ds_read2st64_b32 v[2:3], v199 offset0:80 offset1:88
	ds_read2st64_b32 v[4:5], v199 offset0:208 offset1:216
	v_mov_b32_e32 v8, 0
	v_mov_b32_e32 v7, 0
	v_mov_b32_e32 v6, 0
	s_waitcnt lgkmcnt(0)
	v_fma_f32 v2, v28, v1, v2
	v_fma_f32 v4, v44, v1, v4
	v_fmac_f32_e32 v3, v29, v1
	v_fmac_f32_e32 v5, v45, v1
	ds_write2st64_b32 v199, v2, v3 offset0:80 offset1:88
	ds_write2st64_b32 v199, v4, v5 offset0:208 offset1:216
	ds_read2st64_b32 v[2:3], v199 offset0:96 offset1:104
	ds_read2st64_b32 v[4:5], v199 offset0:224 offset1:232
	v_mov_b32_e32 v29, 0
	v_mov_b32_e32 v28, 0
	v_mov_b32_e32 v27, 0
	s_waitcnt lgkmcnt(0)
	v_fma_f32 v2, v30, v1, v2
	v_fma_f32 v4, v46, v1, v4
	v_fmac_f32_e32 v3, v31, v1
	v_fmac_f32_e32 v5, v47, v1
	ds_write2st64_b32 v199, v2, v3 offset0:96 offset1:104
	ds_write2st64_b32 v199, v4, v5 offset0:224 offset1:232
	ds_read2st64_b32 v[2:3], v199 offset0:112 offset1:120
	ds_read2st64_b32 v[4:5], v199 offset0:240 offset1:248
	v_mov_b32_e32 v31, 0
	v_mov_b32_e32 v30, 0
	v_mov_b32_e32 v26, 0
	s_waitcnt lgkmcnt(0)
	v_fma_f32 v2, v32, v1, v2
	v_fma_f32 v4, v48, v1, v4
	v_fmac_f32_e32 v3, v33, v1
	v_fmac_f32_e32 v5, v49, v1
	v_sub_u32_e64 v1, s83, 8 clamp
	ds_write2st64_b32 v199, v2, v3 offset0:112 offset1:120
	v_readfirstlane_b32 s14, v1
	s_lshl_b64 s[14:15], -1, s14
	s_and_b64 s[4:5], s[4:5], s[14:15]
	ds_write2st64_b32 v199, v4, v5 offset0:240 offset1:248
	v_mov_b32_e32 v1, v179
	s_cmp_eq_u64 s[4:5], 0
	v_mov_b32_e32 v5, 0
	v_mov_b32_e32 v4, 0
	v_mov_b32_e32 v3, 0
	v_mov_b32_e32 v2, 0
	v_mov_b32_e32 v33, 0
	v_mov_b32_e32 v32, 0
	v_mov_b32_e32 v25, 0
	v_mov_b32_e32 v24, 0
	v_mov_b32_e32 v23, 0
	v_mov_b32_e32 v22, 0
	v_mov_b32_e32 v21, 0
	v_mov_b32_e32 v20, 0
	v_mov_b32_e32 v19, 0
	v_mov_b32_e32 v18, 0
	v_mov_b32_e32 v35, 0
	s_cbranch_scc1 .LBB0_285
	s_lshl_b32 s16, s22, 1
	s_add_u32 s14, s47, s16
	s_addc_u32 s15, s48, 0
	s_add_u32 s16, s49, s16
	s_flbit_i32_b64 s18, s[4:5]
	v_ashrrev_i32_e32 v161, 3, v34
	s_addc_u32 s17, s82, 0
	s_xor_b32 s20, s18, 63
	v_lshl_add_u32 v2, s20, 6, v161
	v_ashrrev_i32_e32 v3, 31, v2
	v_lshlrev_b64 v[2:3], 8, v[2:3]
	v_lshlrev_b32_e32 v6, 4, v34
	v_lshl_add_u64 v[4:5], s[16:17], 0, v[2:3]
	v_and_b32_e32 v16, 0x70, v6
	v_mov_b32_e32 v17, v0
	v_lshl_add_u64 v[4:5], v[4:5], 0, v[16:17]
	v_lshl_add_u64 v[2:3], s[14:15], 0, v[2:3]
	v_lshl_add_u64 v[2:3], v[2:3], 0, v[16:17]
	s_waitcnt vmcnt(0)
	global_load_dwordx4 v[130:133], v[4:5], off
	global_load_dwordx4 v[134:137], v[2:3], off
	v_ashrrev_i32_e32 v18, 5, v1
	v_lshrrev_b32_e32 v34, 2, v1
	v_lshlrev_b32_e32 v37, 2, v18
	v_and_b32_e32 v19, 31, v1
	v_lshlrev_b32_e32 v20, 2, v1
	v_and_b32_e32 v21, 16, v1
	v_lshlrev_b32_e32 v22, 3, v1
	v_mov_b32_e32 v14, v0
	v_mov_b32_e32 v15, v0
	s_movk_i32 s18, 0x90
	v_and_or_b32 v34, v34, 3, v37
	v_mov_b32_e32 v1, v0
	v_mov_b32_e32 v2, v0
	v_mov_b32_e32 v3, v0
	v_mov_b32_e32 v4, v0
	v_mov_b32_e32 v5, v0
	v_mov_b32_e32 v6, v0
	v_mov_b32_e32 v7, v0
	v_mov_b32_e32 v8, v0
	v_mov_b32_e32 v9, v0
	v_mov_b32_e32 v10, v0
	v_mov_b32_e32 v11, v0
	v_mov_b32_e32 v12, v0
	v_mov_b32_e32 v13, v0
	v_mul_lo_u32 v35, v161, s18
	v_mul_lo_u32 v36, v161, s70
	v_mul_u32_u24_e32 v38, 0x90, v19
	v_bitop3_b32 v164, v20, s66, v240 bitop3:0x6c
	v_lshlrev_b32_e32 v39, 1, v21
	v_and_b32_e32 v40, 24, v22
	v_lshlrev_b32_e32 v41, 4, v18
	v_mov_b64_e32 v[32:33], v[14:15]
	v_mul_lo_u32 v34, v34, s70
	v_mov_b64_e32 v[30:31], v[12:13]
	v_mov_b64_e32 v[28:29], v[10:11]
	v_mov_b64_e32 v[26:27], v[8:9]
	v_mov_b64_e32 v[24:25], v[6:7]
	v_mov_b64_e32 v[22:23], v[4:5]
	v_mov_b64_e32 v[20:21], v[2:3]
	v_mov_b64_e32 v[18:19], v[0:1]
	v_add3_u32 v165, 0, v35, v16
	v_add3_u32 v166, 0, v36, v16
	v_lshl_add_u64 v[140:141], s[14:15], 0, v[16:17]
	v_add_u32_e32 v34, 0, v34
	s_lshl_b64 s[14:15], 1, s20
	v_lshl_add_u64 v[142:143], s[16:17], 0, v[16:17]
	v_mov_b64_e32 v[16:17], v[14:15]
	v_mul_f32_e32 v162, 0xc3ffc000, v186
	s_mov_b32 s22, 0
	v_mov_b32_e32 v192, 0xefa18f08
	v_mov_b32_e32 v190, 0
	v_sub_u32_e32 v167, v37, v188
	v_add3_u32 v188, 0, v38, v41
	s_add_i32 s23, s83, -8
	v_add3_u32 v191, v34, v39, v40
	s_andn2_b64 s[14:15], s[4:5], s[14:15]
	v_mov_b64_e32 v[14:15], v[12:13]
	v_mov_b64_e32 v[12:13], v[10:11]
	v_mov_b64_e32 v[10:11], v[8:9]
	v_mov_b64_e32 v[8:9], v[6:7]
	v_mov_b64_e32 v[6:7], v[4:5]
	v_mov_b64_e32 v[4:5], v[2:3]
	v_mov_b64_e32 v[2:3], v[0:1]
	s_mov_b64 s[16:17], s[14:15]
	s_mov_b32 s18, 0
	s_cmp_eq_u64 s[16:17], 0
	s_cbranch_scc1 .Lm2_pre_nob1
	s_flbit_i32_b64 s62, s[16:17]
	s_xor_b32 s62, s62, 63
	s_lshl_b64 s[4:5], 1, s62
	s_andn2_b64 s[16:17], s[16:17], s[4:5]
	v_lshl_add_u32 v34, s62, 6, v161
	v_ashrrev_i32_e32 v35, 31, v34
	v_lshlrev_b64 v[34:35], 8, v[34:35]
	v_lshl_add_u64 v[36:37], v[142:143], 0, v[34:35]
	v_lshl_add_u64 v[34:35], v[140:141], 0, v[34:35]
	global_load_dwordx4 v[226:229], v[36:37], off
	global_load_dwordx4 v[230:233], v[34:35], off
	s_mov_b32 s18, 1
	s_waitcnt vmcnt(2)
	s_branch .Lm2_pre_w

; #define LAS __attribute__((address_space(3)))
; template <int MODE  > ...
;     ...
;         const bool has_next = rem != 0ull; int jn = 0;
;         if (has_next) { jn = 63 - __builtin_clzll(rem); rem &= ~(1ull << jn);
;             kreg = *(const u32x4*)(Kg + (size_t)(64 * jn + skey) * 128 + schunk * 8);
;             if (NEEDV) vreg = *(const u32x4*)(Vg + (size_t)(64 * jn + skey) * 128 + schunk * 8); }
;         const bool selbit = (MODE == 1) ? (((selmask >> j) & 1ull) != 0ull) : true;
;         bool active = true;
;         if (MODE == 1) active = __builtin_amdgcn_ballot_w64(selbit) != 0ull;
;         if (active) {
;             const LAS bf16_t* kb = (const LAS bf16_t*)(lds + A_KBUF) + cur * 64 * KPITCH;
;             constexpr int STEP = CMPM ? 16 : 1;
;             const int Bint = CMPM ? (1024 * j + 31 - t + 64 * h) : (64 * j - t + 4 * h);
;             const float sl = slope2 * (float)STEP;
;             const float mref = st.m; const bool fresh = !(mref > -1e28f);
;             const float mest = fresh ? 0.f : mref;
;             const float basef = selbit ? (slope2 * (float)Bint - mest) : -1e30f;
;             int ptype;
;             if (MODE == 1) ptype = (j == cblk) ? 1 : 0;
;             else if (MODE == 2) ptype = (j == cblk) ? 1 : ((j == cblk - 8) ? 2 : 0);
;             else ptype = (64 * j + 63 <= 4 * cblk - 2) ? 0 : 1;
;             f32x16 s0, s1;
;             { const float sl2 = sl + sl, sl3 = sl2 + sl;
; #pragma unroll
;               for (int g8 = 0; g8 < 4; ++g8) {
;                   const float b0 = __builtin_fmaf(sl, (float)(8 * g8), basef), b1 = __builtin_fmaf(sl, (float)(8 * g8 + 32), basef);
;                   s0[4 * g8] = b0; s0[4 * g8 + 1] = b0 + sl; s0[4 * g8 + 2] = b0 + sl2; s0[4 * g8 + 3] = b0 + sl3;
;                   s1[4 * g8] = b1; s1[4 * g8 + 1] = b1 + sl; s1[4 * g8 + 2] = b1 + sl2; s1[4 * g8 + 3] = b1 + sl3;
;               } }
;             if (ptype == 1) {
;                 const float thr = 0.5f * slope2 - mest;
; #pragma unroll
;                 for (int i = 0; i < 16; ++i) { s0[i] = (s0[i] < thr) ? s0[i] : -1e30f; s1[i] = (s1[i] < thr) ? s1[i] : -1e30f; }
;             } else if (ptype == 2) {
;                 const float thr = -511.5f * slope2 - mest;
; #pragma unroll
;                 for (int i = 0; i < 16; ++i) { s0[i] = (s0[i] > thr) ? s0[i] : -1e30f; s1[i] = (s1[i] > thr) ? s1[i] : -1e30f; }
;             }
.Lm2_pre_w:
	s_waitcnt lgkmcnt(0)
	ds_write_b128 v165, v[130:133]
	ds_write_b128 v166, v[134:137] offset:18432
	s_waitcnt lgkmcnt(0)
	s_barrier
.LBB0_268:
	s_mov_b32 s19, 0
	s_cmp_eq_u64 s[16:17], 0
	s_cbranch_scc1 .Lm2_noload
	s_flbit_i32_b64 s4, s[16:17]
	s_xor_b32 s4, s4, 63
	s_lshl_b64 vcc, 1, s4
	s_andn2_b64 s[16:17], s[16:17], vcc
	s_mov_b32 s19, 1
	v_lshl_add_u32 v34, s4, 6, v161
	v_ashrrev_i32_e32 v35, 31, v34
	v_lshlrev_b64 v[34:35], 8, v[34:35]
	v_lshl_add_u64 v[36:37], v[142:143], 0, v[34:35]
	v_lshl_add_u64 v[34:35], v[140:141], 0, v[34:35]
	s_cmp_eq_u32 s22, 0
	s_cbranch_scc0 .Lm2_loadB
	global_load_dwordx4 v[130:133], v[36:37], off
	global_load_dwordx4 v[134:137], v[34:35], off
	s_branch .Lm2_noload
.Lm2_loadB:
	global_load_dwordx4 v[226:229], v[36:37], off
	global_load_dwordx4 v[230:233], v[34:35], off
.Lm2_noload:
.Lm2_body:
	s_mul_i32 vcc_lo, s22, 0x2400
	s_mul_i32 vcc_hi, s22, 0x3000
	v_add_u32_e32 v223, vcc_lo, v188
	v_add_u32_e32 v222, vcc_hi, v191
	ds_read_b128 v[66:69], v223
	ds_read_b128 v[70:73], v223 offset:4608
	ds_read_b128 v[74:77], v223 offset:32
	ds_read_b128 v[78:81], v223 offset:4640
	ds_read_b128 v[82:85], v223 offset:64
	ds_read_b128 v[86:89], v223 offset:4672
	ds_read_b128 v[90:93], v223 offset:96
	ds_read_b128 v[94:97], v223 offset:4704
	v_lshl_add_u32 v1, s20, 6, v167
	v_cvt_f32_i32_e32 v50, v1
	v_cmp_nlt_f32_e64 s[14:15], s71, v192
	s_cmp_eq_u32 s20, s23
	s_cselect_b32 s21, 2, 0
	s_cmp_lg_u32 s20, s83
	s_cselect_b32 s68, s21, 1
	s_cmp_eq_u32 s68, 0
	v_cndmask_b32_e64 v1, v192, 0, s[14:15]
	v_fma_f32 v62, v186, v50, -v1
	v_fma_f32 v34, 0, v186, v62
	v_fmamk_f32 v38, v186, 0x41000000, v62
	v_fmamk_f32 v42, v186, 0x41800000, v62
	v_fmamk_f32 v46, v186, 0x41c00000, v62
	v_fmamk_f32 v50, v186, 0x42000000, v62
	v_fmamk_f32 v54, v186, 0x42200000, v62
	v_fmamk_f32 v58, v186, 0x42400000, v62
	v_fmac_f32_e32 v62, 0x42600000, v186
	v_add_f32_e32 v35, v186, v34
	v_add_f32_e32 v36, v187, v34
	v_add_f32_e32 v37, v163, v34
	v_add_f32_e32 v39, v186, v38
	v_add_f32_e32 v40, v187, v38
	v_add_f32_e32 v41, v163, v38
	v_add_f32_e32 v43, v186, v42
	v_add_f32_e32 v44, v187, v42
	v_add_f32_e32 v45, v163, v42
	v_add_f32_e32 v47, v186, v46
	v_add_f32_e32 v48, v187, v46
	v_add_f32_e32 v49, v163, v46
	v_add_f32_e32 v51, v186, v50
	v_add_f32_e32 v52, v187, v50
	v_add_f32_e32 v53, v163, v50
	v_add_f32_e32 v55, v186, v54
	v_add_f32_e32 v56, v187, v54
	v_add_f32_e32 v57, v163, v54
	v_add_f32_e32 v59, v186, v58
	v_add_f32_e32 v60, v187, v58
	v_add_f32_e32 v61, v163, v58
	v_add_f32_e32 v63, v186, v62
	v_add_f32_e32 v64, v187, v62
	v_add_f32_e32 v65, v163, v62
	s_cbranch_scc1 .Lm2_qk
	s_cmp_eq_u32 s68, 1
	s_cbranch_scc1 .Lm2_edge1
	v_sub_f32_e32 v224, v162, v1
	v_cmp_gt_f32_e32 vcc, v34, v224
	s_nop 1
	v_cndmask_b32_e32 v34, v241, v34, vcc
	v_cmp_gt_f32_e32 vcc, v35, v224
	s_nop 1
	v_cndmask_b32_e32 v35, v241, v35, vcc
	v_cmp_gt_f32_e32 vcc, v36, v224
	s_nop 1
	v_cndmask_b32_e32 v36, v241, v36, vcc
	v_cmp_gt_f32_e32 vcc, v37, v224
	s_nop 1
	v_cndmask_b32_e32 v37, v241, v37, vcc
	v_cmp_gt_f32_e32 vcc, v38, v224
	s_nop 1
	v_cndmask_b32_e32 v38, v241, v38, vcc
	v_cmp_gt_f32_e32 vcc, v39, v224
	s_nop 1
	v_cndmask_b32_e32 v39, v241, v39, vcc
	v_cmp_gt_f32_e32 vcc, v40, v224
	s_nop 1
	v_cndmask_b32_e32 v40, v241, v40, vcc
	v_cmp_gt_f32_e32 vcc, v41, v224
	s_nop 1
	v_cndmask_b32_e32 v41, v241, v41, vcc
	v_cmp_gt_f32_e32 vcc, v42, v224
	s_nop 1
	v_cndmask_b32_e32 v42, v241, v42, vcc
	v_cmp_gt_f32_e32 vcc, v43, v224
	s_nop 1
	v_cndmask_b32_e32 v43, v241, v43, vcc
	v_cmp_gt_f32_e32 vcc, v44, v224
	s_nop 1
	v_cndmask_b32_e32 v44, v241, v44, vcc
	v_cmp_gt_f32_e32 vcc, v45, v224
	s_nop 1
	v_cndmask_b32_e32 v45, v241, v45, vcc
	v_cmp_gt_f32_e32 vcc, v46, v224
	s_nop 1
	v_cndmask_b32_e32 v46, v241, v46, vcc
	v_cmp_gt_f32_e32 vcc, v47, v224
	s_nop 1
	v_cndmask_b32_e32 v47, v241, v47, vcc
	v_cmp_gt_f32_e32 vcc, v48, v224
	s_nop 1
	v_cndmask_b32_e32 v48, v241, v48, vcc
	v_cmp_gt_f32_e32 vcc, v49, v224
	s_nop 1
	v_cndmask_b32_e32 v49, v241, v49, vcc
	v_cmp_gt_f32_e32 vcc, v50, v224
	s_nop 1
	v_cndmask_b32_e32 v50, v241, v50, vcc
	v_cmp_gt_f32_e32 vcc, v51, v224
	s_nop 1
	v_cndmask_b32_e32 v51, v241, v51, vcc
	v_cmp_gt_f32_e32 vcc, v52, v224
	s_nop 1
	v_cndmask_b32_e32 v52, v241, v52, vcc
	v_cmp_gt_f32_e32 vcc, v53, v224
	s_nop 1
	v_cndmask_b32_e32 v53, v241, v53, vcc
	v_cmp_gt_f32_e32 vcc, v54, v224
	s_nop 1
	v_cndmask_b32_e32 v54, v241, v54, vcc
	v_cmp_gt_f32_e32 vcc, v55, v224
	s_nop 1
	v_cndmask_b32_e32 v55, v241, v55, vcc
	v_cmp_gt_f32_e32 vcc, v56, v224
	s_nop 1
	v_cndmask_b32_e32 v56, v241, v56, vcc
	v_cmp_gt_f32_e32 vcc, v57, v224
	s_nop 1
	v_cndmask_b32_e32 v57, v241, v57, vcc
	v_cmp_gt_f32_e32 vcc, v58, v224
	s_nop 1
	v_cndmask_b32_e32 v58, v241, v58, vcc
	v_cmp_gt_f32_e32 vcc, v59, v224
	s_nop 1
	v_cndmask_b32_e32 v59, v241, v59, vcc
	v_cmp_gt_f32_e32 vcc, v60, v224
	s_nop 1
	v_cndmask_b32_e32 v60, v241, v60, vcc
	v_cmp_gt_f32_e32 vcc, v61, v224
	s_nop 1
	v_cndmask_b32_e32 v61, v241, v61, vcc
	v_cmp_gt_f32_e32 vcc, v62, v224
	s_nop 1
	v_cndmask_b32_e32 v62, v241, v62, vcc
	v_cmp_gt_f32_e32 vcc, v63, v224
	s_nop 1
	v_cndmask_b32_e32 v63, v241, v63, vcc
	v_cmp_gt_f32_e32 vcc, v64, v224
	s_nop 1
	v_cndmask_b32_e32 v64, v241, v64, vcc
	v_cmp_gt_f32_e32 vcc, v65, v224
	s_nop 1
	v_cndmask_b32_e32 v65, v241, v65, vcc
	s_branch .Lm2_qk
; #define LAS __attribute__((address_space(3)))
; __device__ __forceinline__ float shflx(float v, int mask, int lane) { return __builtin_bit_cast(float, __builtin_amdgcn_ds_bpermute(((lane ^ mask) & 63) << 2, __builtin_bit_cast(int, v))); }
; template <int MODE  > ...
;     ...
;                 for (int i = 0; i < 16; ++i) { s0[i] = (s0[i] < thr) ? s0[i] : -1e30f; s1[i] = (s1[i] < thr) ? s1[i] : -1e30f; }
;             } else if (ptype == 2) {
;                 const float thr = -511.5f * slope2 - mest;
; #pragma unroll
;                 for (int i = 0; i < 16; ++i) { s0[i] = (s0[i] > thr) ? s0[i] : -1e30f; s1[i] = (s1[i] > thr) ? s1[i] : -1e30f; }
;             }
; #pragma unroll
;             for (int kk = 0; kk < 4; ++kk) {
;                 const bf16x8 k0 = *(const LAS bf16x8*)(kb + col * KPITCH + kk * 16 + h * 8);
;                 const bf16x8 k1 = *(const LAS bf16x8*)(kb + (32 + col) * KPITCH + kk * 16 + h * 8);
;                 s0 = __builtin_amdgcn_mfma_f32_32x32x16_bf16(k0, qf[kk], s0, 0, 0, 0);
;                 s1 = __builtin_amdgcn_mfma_f32_32x32x16_bf16(k1, qf[kk], s1, 0, 0, 0);
;             }
;             if (MODE != 3) {
;                 float mx = fmaxf(s0[0], s1[0]);
; #pragma unroll
;                 for (int i = 1; i < 16; ++i) mx = fmaxf(mx, fmaxf(s0[i], s1[i]));
;                 mx = fmaxf(mx, shflx(mx, 32, lane));
;                 float alpha = 1.f;
;                 if (__builtin_amdgcn_ballot_w64(fresh || mx > 0.f) != 0ull) {
;     ...
;                 const LAS bf16_t* vb = (const LAS bf16_t*)(lds + A_VBUF) + cur * 64 * VPITCH + (4 * h + ((lane & 15) >> 2)) * VPITCH + ((lane >> 4) & 1) * 16 + 4 * (lane & 3);
; #pragma unroll
;                 for (int kk = 0; kk < 4; ++kk) {
;                     typedef short v4i16_t __attribute__((ext_vector_type(4)));
;                     const v4i16_t a0 = __builtin_amdgcn_ds_read_tr16_b64_v4i16((LAS v4i16_t*)(vb + (16 * kk) * VPITCH));
;                     const v4i16_t a1 = __builtin_amdgcn_ds_read_tr16_b64_v4i16((LAS v4i16_t*)(vb + (16 * kk + 8) * VPITCH));
;                     const v4i16_t b0 = __builtin_amdgcn_ds_read_tr16_b64_v4i16((LAS v4i16_t*)(vb + (16 * kk) * VPITCH + 32));
;                     const v4i16_t b1 = __builtin_amdgcn_ds_read_tr16_b64_v4i16((LAS v4i16_t*)(vb + (16 * kk + 8) * VPITCH + 32));
.Lm2_edge1:
	v_sub_f32_e32 v224, v189, v1
	v_cmp_lt_f32_e32 vcc, v34, v224
	s_nop 1
	v_cndmask_b32_e32 v34, v241, v34, vcc
	v_cmp_lt_f32_e32 vcc, v35, v224
	s_nop 1
	v_cndmask_b32_e32 v35, v241, v35, vcc
	v_cmp_lt_f32_e32 vcc, v36, v224
	s_nop 1
	v_cndmask_b32_e32 v36, v241, v36, vcc
	v_cmp_lt_f32_e32 vcc, v37, v224
	s_nop 1
	v_cndmask_b32_e32 v37, v241, v37, vcc
	v_cmp_lt_f32_e32 vcc, v38, v224
	s_nop 1
	v_cndmask_b32_e32 v38, v241, v38, vcc
	v_cmp_lt_f32_e32 vcc, v39, v224
	s_nop 1
	v_cndmask_b32_e32 v39, v241, v39, vcc
	v_cmp_lt_f32_e32 vcc, v40, v224
	s_nop 1
	v_cndmask_b32_e32 v40, v241, v40, vcc
	v_cmp_lt_f32_e32 vcc, v41, v224
	s_nop 1
	v_cndmask_b32_e32 v41, v241, v41, vcc
	v_cmp_lt_f32_e32 vcc, v42, v224
	s_nop 1
	v_cndmask_b32_e32 v42, v241, v42, vcc
	v_cmp_lt_f32_e32 vcc, v43, v224
	s_nop 1
	v_cndmask_b32_e32 v43, v241, v43, vcc
	v_cmp_lt_f32_e32 vcc, v44, v224
	s_nop 1
	v_cndmask_b32_e32 v44, v241, v44, vcc
	v_cmp_lt_f32_e32 vcc, v45, v224
	s_nop 1
	v_cndmask_b32_e32 v45, v241, v45, vcc
	v_cmp_lt_f32_e32 vcc, v46, v224
	s_nop 1
	v_cndmask_b32_e32 v46, v241, v46, vcc
	v_cmp_lt_f32_e32 vcc, v47, v224
	s_nop 1
	v_cndmask_b32_e32 v47, v241, v47, vcc
	v_cmp_lt_f32_e32 vcc, v48, v224
	s_nop 1
	v_cndmask_b32_e32 v48, v241, v48, vcc
	v_cmp_lt_f32_e32 vcc, v49, v224
	s_nop 1
	v_cndmask_b32_e32 v49, v241, v49, vcc
	v_cmp_lt_f32_e32 vcc, v50, v224
	s_nop 1
	v_cndmask_b32_e32 v50, v241, v50, vcc
	v_cmp_lt_f32_e32 vcc, v51, v224
	s_nop 1
	v_cndmask_b32_e32 v51, v241, v51, vcc
	v_cmp_lt_f32_e32 vcc, v52, v224
	s_nop 1
	v_cndmask_b32_e32 v52, v241, v52, vcc
	v_cmp_lt_f32_e32 vcc, v53, v224
	s_nop 1
	v_cndmask_b32_e32 v53, v241, v53, vcc
	v_cmp_lt_f32_e32 vcc, v54, v224
	s_nop 1
	v_cndmask_b32_e32 v54, v241, v54, vcc
	v_cmp_lt_f32_e32 vcc, v55, v224
	s_nop 1
	v_cndmask_b32_e32 v55, v241, v55, vcc
	v_cmp_lt_f32_e32 vcc, v56, v224
	s_nop 1
	v_cndmask_b32_e32 v56, v241, v56, vcc
	v_cmp_lt_f32_e32 vcc, v57, v224
	s_nop 1
	v_cndmask_b32_e32 v57, v241, v57, vcc
	v_cmp_lt_f32_e32 vcc, v58, v224
	s_nop 1
	v_cndmask_b32_e32 v58, v241, v58, vcc
	v_cmp_lt_f32_e32 vcc, v59, v224
	s_nop 1
	v_cndmask_b32_e32 v59, v241, v59, vcc
	v_cmp_lt_f32_e32 vcc, v60, v224
	s_nop 1
	v_cndmask_b32_e32 v60, v241, v60, vcc
	v_cmp_lt_f32_e32 vcc, v61, v224
	s_nop 1
	v_cndmask_b32_e32 v61, v241, v61, vcc
	v_cmp_lt_f32_e32 vcc, v62, v224
	s_nop 1
	v_cndmask_b32_e32 v62, v241, v62, vcc
	v_cmp_lt_f32_e32 vcc, v63, v224
	s_nop 1
	v_cndmask_b32_e32 v63, v241, v63, vcc
	v_cmp_lt_f32_e32 vcc, v64, v224
	s_nop 1
	v_cndmask_b32_e32 v64, v241, v64, vcc
	v_cmp_lt_f32_e32 vcc, v65, v224
	s_nop 1
	v_cndmask_b32_e32 v65, v241, v65, vcc
.Lm2_qk:
	s_waitcnt lgkmcnt(7)
	v_mfma_f32_32x32x16_bf16 v[34:49], v[66:69], v[144:147], v[34:49]
	s_waitcnt lgkmcnt(6)
	v_mfma_f32_32x32x16_bf16 v[50:65], v[70:73], v[144:147], v[50:65]
	s_waitcnt lgkmcnt(5)
	v_mfma_f32_32x32x16_bf16 v[34:49], v[74:77], v[148:151], v[34:49]
	s_waitcnt lgkmcnt(4)
	v_mfma_f32_32x32x16_bf16 v[50:65], v[78:81], v[148:151], v[50:65]
	s_waitcnt lgkmcnt(3)
	v_mfma_f32_32x32x16_bf16 v[34:49], v[82:85], v[152:155], v[34:49]
	s_waitcnt lgkmcnt(2)
	v_mfma_f32_32x32x16_bf16 v[50:65], v[86:89], v[152:155], v[50:65]
	s_waitcnt lgkmcnt(1)
	v_mfma_f32_32x32x16_bf16 v[34:49], v[90:93], v[156:159], v[34:49]
	s_waitcnt lgkmcnt(0)
	v_mfma_f32_32x32x16_bf16 v[50:65], v[94:97], v[156:159], v[50:65]
	ds_read_b64_tr_b16 v[66:67], v222 offset:18432
	ds_read_b64_tr_b16 v[68:69], v222 offset:19968
	ds_read_b64_tr_b16 v[70:71], v222 offset:18496
	ds_read_b64_tr_b16 v[72:73], v222 offset:20032
	ds_read_b64_tr_b16 v[74:75], v222 offset:21504
	ds_read_b64_tr_b16 v[76:77], v222 offset:23040
	ds_read_b64_tr_b16 v[78:79], v222 offset:21568
	ds_read_b64_tr_b16 v[80:81], v222 offset:23104
	s_nop 3
	v_max3_f32 v220, v34, v35, v36
	v_max3_f32 v220, v220, v37, v38
	v_max3_f32 v220, v220, v39, v40
	v_max3_f32 v220, v220, v41, v42
	v_max3_f32 v220, v220, v43, v44
	v_max3_f32 v220, v220, v45, v46
	v_max3_f32 v220, v220, v47, v48
	v_max3_f32 v221, v50, v51, v52
	v_max3_f32 v221, v221, v53, v54
	v_max3_f32 v221, v221, v55, v56
	v_max3_f32 v221, v221, v57, v58
	v_max3_f32 v221, v221, v59, v60
	v_max3_f32 v221, v221, v61, v62
	v_max3_f32 v221, v221, v63, v64
	v_max3_f32 v220, v220, v49, v65
	v_max_f32_e32 v220, v220, v221
	ds_bpermute_b32 v221, v164, v220
	ds_read_b64_tr_b16 v[82:83], v222 offset:24576
	ds_read_b64_tr_b16 v[84:85], v222 offset:26112
	ds_read_b64_tr_b16 v[86:87], v222 offset:24640
	ds_read_b64_tr_b16 v[88:89], v222 offset:26176
	ds_read_b64_tr_b16 v[90:91], v222 offset:27648
	ds_read_b64_tr_b16 v[92:93], v222 offset:29184
	ds_read_b64_tr_b16 v[94:95], v222 offset:27712
	ds_read_b64_tr_b16 v[96:97], v222 offset:29248
	s_waitcnt lgkmcnt(8)
	v_max_f32_e32 v220, v220, v221
	v_cmp_lt_f32_e32 vcc, 0, v220
	s_or_b64 vcc, s[14:15], vcc
	s_cbranch_vccz .Lm2_norescale
; #define LAS __attribute__((address_space(3)))
; template <int MODE  > ...
;     ...
;                 if (__builtin_amdgcn_ballot_w64(fresh || mx > 0.f) != 0ull) {
;                     const float moldr = fresh ? -1e29f : 0.f, mnewr = fmaxf(moldr, mx);
;                     alpha = __builtin_amdgcn_exp2f(moldr - mnewr);
;                     st.m = mest + mnewr;
; #pragma unroll
;                     for (int i = 0; i < 16; ++i) { s0[i] = __builtin_amdgcn_exp2f(s0[i] - mnewr); s1[i] = __builtin_amdgcn_exp2f(s1[i] - mnewr); }
;                     st.o0 *= alpha; st.o1 *= alpha;
;                 } else {
; #pragma unroll
;                     for (int i = 0; i < 16; ++i) { s0[i] = __builtin_amdgcn_exp2f(s0[i]); s1[i] = __builtin_amdgcn_exp2f(s1[i]); }
;                 }
;                 { typedef float f32x8 __attribute__((ext_vector_type(8)));
;                   const f32x16 t16 = s0 + s1;
;                   const f32x8 t8 = __builtin_shufflevector(t16, t16, 0, 1, 2, 3, 4, 5, 6, 7) + __builtin_shufflevector(t16, t16, 8, 9, 10, 11, 12, 13, 14, 15);
;                   const f32x4 t4 = __builtin_shufflevector(t8, t8, 0, 1, 2, 3) + __builtin_shufflevector(t8, t8, 4, 5, 6, 7);
;                   float ps = (t4[0] + t4[1]) + (t4[2] + t4[3]);
;                   ps += shflx(ps, 32, lane);
;                   st.l = st.l * alpha + ps; }
;                 bf16x8 pf[4];
; #pragma unroll
;                 for (int kk = 0; kk < 4; ++kk) {
;                     u32x4 pw;
;                     if (kk < 2) { pw.x = pk2(s0[8 * kk], s0[8 * kk + 1]); pw.y = pk2(s0[8 * kk + 2], s0[8 * kk + 3]); pw.z = pk2(s0[8 * kk + 4], s0[8 * kk + 5]); pw.w = pk2(s0[8 * kk + 6], s0[8 * kk + 7]); }
;                     else { const int k2 = kk - 2; pw.x = pk2(s1[8 * k2], s1[8 * k2 + 1]); pw.y = pk2(s1[8 * k2 + 2], s1[8 * k2 + 3]); pw.z = pk2(s1[8 * k2 + 4], s1[8 * k2 + 5]); pw.w = pk2(s1[8 * k2 + 6], s1[8 * k2 + 7]); }
;                     pf[kk] = __builtin_bit_cast(bf16x8, pw);
;                 }
;                 const LAS bf16_t* vb = (const LAS bf16_t*)(lds + A_VBUF) + cur * 64 * VPITCH + (4 * h + ((lane & 15) >> 2)) * VPITCH + ((lane >> 4) & 1) * 16 + 4 * (lane & 3);
; #pragma unroll
;                 for (int kk = 0; kk < 4; ++kk) {
;                     typedef short v4i16_t __attribute__((ext_vector_type(4)));
	v_cndmask_b32_e64 v221, 0, v242, s[14:15]
	v_max_f32_e32 v220, v221, v220
	v_sub_f32_e32 v221, v221, v220
	v_exp_f32_e32 v160, v221
	v_add_f32_e32 v192, v1, v220
	v_sub_f32_e32 v114, v34, v220
	v_exp_f32_e32 v114, v114
	v_sub_f32_e32 v98, v50, v220
	v_exp_f32_e32 v98, v98
	v_sub_f32_e32 v115, v35, v220
	v_exp_f32_e32 v115, v115
	v_sub_f32_e32 v99, v51, v220
	v_exp_f32_e32 v99, v99
	v_sub_f32_e32 v116, v36, v220
	v_exp_f32_e32 v116, v116
	v_sub_f32_e32 v100, v52, v220
	v_exp_f32_e32 v100, v100
	v_sub_f32_e32 v117, v37, v220
	v_exp_f32_e32 v117, v117
	v_sub_f32_e32 v101, v53, v220
	v_exp_f32_e32 v101, v101
	v_sub_f32_e32 v118, v38, v220
	v_exp_f32_e32 v118, v118
	v_sub_f32_e32 v102, v54, v220
	v_exp_f32_e32 v102, v102
	v_sub_f32_e32 v119, v39, v220
	v_exp_f32_e32 v119, v119
	v_sub_f32_e32 v103, v55, v220
	v_exp_f32_e32 v103, v103
	v_sub_f32_e32 v120, v40, v220
	v_exp_f32_e32 v120, v120
	v_sub_f32_e32 v104, v56, v220
	v_exp_f32_e32 v104, v104
	v_sub_f32_e32 v121, v41, v220
	v_exp_f32_e32 v121, v121
	v_sub_f32_e32 v105, v57, v220
	v_exp_f32_e32 v105, v105
	v_sub_f32_e32 v122, v42, v220
	v_exp_f32_e32 v122, v122
	v_sub_f32_e32 v106, v58, v220
	v_exp_f32_e32 v106, v106
	v_sub_f32_e32 v123, v43, v220
	v_exp_f32_e32 v123, v123
	v_sub_f32_e32 v107, v59, v220
	v_exp_f32_e32 v107, v107
	v_sub_f32_e32 v124, v44, v220
	v_exp_f32_e32 v124, v124
	v_sub_f32_e32 v108, v60, v220
	v_exp_f32_e32 v108, v108
	v_sub_f32_e32 v125, v45, v220
	v_exp_f32_e32 v125, v125
	v_sub_f32_e32 v109, v61, v220
	v_exp_f32_e32 v109, v109
	v_sub_f32_e32 v126, v46, v220
	v_exp_f32_e32 v126, v126
	v_sub_f32_e32 v110, v62, v220
	v_exp_f32_e32 v110, v110
	v_sub_f32_e32 v127, v47, v220
	v_exp_f32_e32 v127, v127
	v_sub_f32_e32 v111, v63, v220
	v_exp_f32_e32 v111, v111
	v_sub_f32_e32 v128, v48, v220
	v_exp_f32_e32 v128, v128
	v_sub_f32_e32 v112, v64, v220
	v_exp_f32_e32 v112, v112
	v_sub_f32_e32 v129, v49, v220
	v_exp_f32_e32 v129, v129
	v_sub_f32_e32 v113, v65, v220
	v_exp_f32_e32 v113, v113
	v_pk_mul_f32 v[18:19], v[18:19], v[160:161] op_sel_hi:[1,0]
	v_pk_mul_f32 v[20:21], v[20:21], v[160:161] op_sel_hi:[1,0]
	v_pk_mul_f32 v[22:23], v[22:23], v[160:161] op_sel_hi:[1,0]
	v_pk_mul_f32 v[24:25], v[24:25], v[160:161] op_sel_hi:[1,0]
	v_pk_mul_f32 v[26:27], v[26:27], v[160:161] op_sel_hi:[1,0]
	v_pk_mul_f32 v[28:29], v[28:29], v[160:161] op_sel_hi:[1,0]
	v_pk_mul_f32 v[30:31], v[30:31], v[160:161] op_sel_hi:[1,0]
	v_pk_mul_f32 v[32:33], v[32:33], v[160:161] op_sel_hi:[1,0]
	v_pk_mul_f32 v[2:3], v[2:3], v[160:161] op_sel_hi:[1,0]
	v_pk_mul_f32 v[4:5], v[4:5], v[160:161] op_sel_hi:[1,0]
	v_pk_mul_f32 v[6:7], v[6:7], v[160:161] op_sel_hi:[1,0]
	v_pk_mul_f32 v[8:9], v[8:9], v[160:161] op_sel_hi:[1,0]
	v_pk_mul_f32 v[10:11], v[10:11], v[160:161] op_sel_hi:[1,0]
	v_pk_mul_f32 v[12:13], v[12:13], v[160:161] op_sel_hi:[1,0]
	v_pk_mul_f32 v[14:15], v[14:15], v[160:161] op_sel_hi:[1,0]
	v_pk_mul_f32 v[16:17], v[16:17], v[160:161] op_sel_hi:[1,0]
	s_branch .Lm2_pv
.Lm2_norescale:
	v_exp_f32_e32 v114, v34
	v_exp_f32_e32 v98, v50
	v_exp_f32_e32 v115, v35
	v_exp_f32_e32 v99, v51
	v_exp_f32_e32 v116, v36
	v_exp_f32_e32 v100, v52
	v_exp_f32_e32 v117, v37
	v_exp_f32_e32 v101, v53
	v_exp_f32_e32 v118, v38
	v_exp_f32_e32 v102, v54
	v_exp_f32_e32 v119, v39
	v_exp_f32_e32 v103, v55
	v_exp_f32_e32 v120, v40
	v_exp_f32_e32 v104, v56
	v_exp_f32_e32 v121, v41
	v_exp_f32_e32 v105, v57
	v_exp_f32_e32 v122, v42
	v_exp_f32_e32 v106, v58
	v_exp_f32_e32 v123, v43
	v_exp_f32_e32 v107, v59
	v_exp_f32_e32 v124, v44
	v_exp_f32_e32 v108, v60
	v_exp_f32_e32 v125, v45
	v_exp_f32_e32 v109, v61
	v_exp_f32_e32 v126, v46
	v_exp_f32_e32 v110, v62
	v_exp_f32_e32 v127, v47
	v_exp_f32_e32 v111, v63
	v_exp_f32_e32 v128, v48
	v_exp_f32_e32 v112, v64
	v_exp_f32_e32 v129, v49
	v_exp_f32_e32 v113, v65
	v_mov_b32_e32 v160, 1.0
.Lm2_pv:
	v_cvt_pk_bf16_f32 v34, v114, v115
	v_cvt_pk_bf16_f32 v35, v116, v117
	v_cvt_pk_bf16_f32 v36, v118, v119
	v_cvt_pk_bf16_f32 v37, v120, v121
	s_waitcnt lgkmcnt(0)
	s_nop 0
	v_mfma_f32_32x32x16_bf16 v[18:33], v[66:69], v[34:37], v[18:33]
	v_mfma_f32_32x32x16_bf16 v[2:17], v[70:73], v[34:37], v[2:17]
	v_cvt_pk_bf16_f32 v38, v122, v123
	v_cvt_pk_bf16_f32 v39, v124, v125
	v_cvt_pk_bf16_f32 v40, v126, v127
	v_cvt_pk_bf16_f32 v41, v128, v129
	v_pk_add_f32 v[64:65], v[98:99], v[114:115]
	v_pk_add_f32 v[62:63], v[102:103], v[118:119]
	v_pk_add_f32 v[50:51], v[106:107], v[122:123]
	v_pk_add_f32 v[60:61], v[110:111], v[126:127]
	v_pk_add_f32 v[58:59], v[104:105], v[120:121]
	v_mfma_f32_32x32x16_bf16 v[18:33], v[74:77], v[38:41], v[18:33]
	v_mfma_f32_32x32x16_bf16 v[2:17], v[78:81], v[38:41], v[2:17]
	v_cvt_pk_bf16_f32 v42, v98, v99
	v_cvt_pk_bf16_f32 v43, v100, v101
	v_cvt_pk_bf16_f32 v44, v102, v103
	v_cvt_pk_bf16_f32 v45, v104, v105
	v_pk_add_f32 v[56:57], v[112:113], v[128:129]
	v_pk_add_f32 v[52:53], v[108:109], v[124:125]
	v_pk_add_f32 v[54:55], v[100:101], v[116:117]
	v_pk_add_f32 v[60:61], v[62:63], v[60:61]
	v_pk_add_f32 v[50:51], v[64:65], v[50:51]
	v_mfma_f32_32x32x16_bf16 v[18:33], v[82:85], v[42:45], v[18:33]
	v_mfma_f32_32x32x16_bf16 v[2:17], v[86:89], v[42:45], v[2:17]
	v_cvt_pk_bf16_f32 v46, v106, v107
	v_cvt_pk_bf16_f32 v47, v108, v109
	v_cvt_pk_bf16_f32 v48, v110, v111
	v_cvt_pk_bf16_f32 v49, v112, v113
	v_pk_add_f32 v[56:57], v[58:59], v[56:57]
	v_pk_add_f32 v[52:53], v[54:55], v[52:53]
	v_pk_add_f32 v[50:51], v[50:51], v[60:61]
	v_pk_add_f32 v[52:53], v[52:53], v[56:57]
	v_mfma_f32_32x32x16_bf16 v[18:33], v[90:93], v[46:49], v[18:33]
	v_mfma_f32_32x32x16_bf16 v[2:17], v[94:97], v[46:49], v[2:17]
	v_add_f32_e32 v50, v50, v51
	v_add_f32_e32 v51, v52, v53
	v_add_f32_e32 v50, v50, v51
	ds_bpermute_b32 v51, v164, v50
	s_waitcnt lgkmcnt(0)
	v_add_f32_e32 v50, v50, v51
	v_fmac_f32_e32 v50, v190, v160
	v_mov_b32_e32 v190, v50
.Lm2_stage:
	s_cmp_eq_u32 s18, 0
	s_cbranch_scc1 .Lm2_bot
	s_lshl_b32 s14, s22, 6
	s_xor_b32 s14, s14, 64
	s_mul_i32 s15, s14, 0x90
	v_add_u32_e32 v34, s15, v165
	s_mulk_i32 s14, 0xc0
	v_add_u32_e32 v35, s14, v166
	s_cmp_eq_u32 s19, 0
	s_cbranch_scc1 .Lm2_w0
	s_waitcnt vmcnt(2)
	s_branch .Lm2_w1

; #define LAS __attribute__((address_space(3)))
; template <int MODE  > ...
;     ...
;         if (has_next) {
;             LAS bf16_t* kb = (LAS bf16_t*)(lds + A_KBUF) + (cur ^ 1) * 64 * KPITCH;
;             *(LAS u32x4*)(kb + skey * KPITCH + schunk * 8) = kreg;
;             if (NEEDV) { LAS bf16_t* vb = (LAS bf16_t*)(lds + A_VBUF) + (cur ^ 1) * 64 * VPITCH;
;                 *(LAS u32x4*)(vb + skey * VPITCH + schunk * 8) = vreg; }
;         }
;         __syncthreads();
;         if (!has_next) break;
;         j = jn; cur ^= 1;
;     }
.Lm2_w1:
	s_cmp_eq_u32 s22, 0
	s_cbranch_scc0 .Lm2_stA
	ds_write_b128 v34, v[226:229]
	ds_write_b128 v35, v[230:233] offset:18432
	s_branch .Lm2_bot
.Lm2_stA:
	ds_write_b128 v34, v[130:133]
	ds_write_b128 v35, v[134:137] offset:18432
.Lm2_bot:
	s_xor_b32 s22, s22, 1
	s_waitcnt lgkmcnt(0)
	s_barrier
	s_cmp_eq_u32 s18, 0
	s_cbranch_scc1 .Lm2_exit
	s_mov_b32 s20, s62
	s_mov_b32 s62, s4
	s_mov_b32 s18, s19
	s_branch .LBB0_268
.Lm2_exit:
	s_nop 11
	v_mov_b32_e32 v35, v190
